# v130 plus waves 4-7 enter the attention j-loop ~0.25us late (s_sleep 8) to de-phase the two waves of each SIMD
# speedup vs baseline: 1.0093x; 1.0093x over previous
; #define PROBE_BEGIN(id) unsigned long long pb_t0_##id = 0; if (PROBE_SEC == (id)) pb_t0_##id = __builtin_amdgcn_s_memrealtime();
; #define LAS __attribute__((address_space(3)))
; __device__ __forceinline__ void attn_compute(Frame& F, int id) {
;     const int b = id >> 5, n = (id >> 1) & 15, kvh = id & 1;
;     LAS unsigned char* lds = F.lds;
;     const bf16* Q = (const bf16*)(F.ws + WS_Q); const bf16* ZA = (const bf16*)(F.ws + WS_ZA);
;     bf16* A5 = (bf16*)(F.ws + WS_A5);
;     const float* sink = F.in[4];
;     const int lane = F.lane, wid = F.wave;
;     const int key0 = 128 * (n - 1);
;     PROBE_BEGIN(4)
;     const int g = wid >> 1, qh = wid & 1, h = kvh * 4 + g, r = lane & 31, hh = lane >> 5;
;     const float sk = sink[h] * LOG2E;
;     const size_t tok0 = (size_t)b * SEQ + 128 * n + 64 * qh + r;
;     bf16x8 qf[2][4];
; #pragma unroll
;     for (int qb = 0; qb < 2; ++qb)
; #pragma unroll
;         for (int st = 0; st < 4; ++st) qf[qb][st] = *(const bf16x8*)(Q + (tok0 + 32 * qb) * 512 + h * 64 + 16 * st + 8 * hh);
;     const LAS f32x4* BT4 = (const LAS f32x4*)(lds + OFF_B);
;     const int ktA = 2 * qh;
;     const LAS f32x4* BTg = BT4 + g * NBT + 63 - r + 4 * hh;
;     const LAS unsigned char* kbase = lds + OFF_K + (32 * ktA + r) * KROW + 16 * hh;
;     const LAS unsigned char* vbase = lds + OFF_V + r * VROW + (32 * ktA + 4 * hh) * 2;
;     float m0 = sk, m1 = sk, l0 = 0.f, l1 = 0.f;
;     f32x16 O0[2], O1[2];
; #pragma unroll
;     for (int q = 0; q < 16; ++q) { O0[0][q] = 0.f; O0[1][q] = 0.f; O1[0][q] = 0.f; O1[1][q] = 0.f; }
; #pragma unroll 1
;     for (int j = 0; j < 9; ++j) {
.LBB0_574:
	v_readfirstlane_b32 s4, v0
	s_nop 3
	s_bitcmp1_b32 s4, 8
	s_cbranch_scc0 .Lattn_lo_half
	s_setprio 1
	s_sleep 8
